# grid barrier: XCD leader publishes the per-XCD generation flag before its own cache invalidate (followers wake ~1.7us earlier), on top of G1 epilogue changes
# baseline (speedup 1.0000x reference)
.LBB0_18:
	s_or_b64 exec, exec, s[4:5]
	buffer_inv sc1
	s_waitcnt vmcnt(0)

.LBB0_344:
	s_or_b64 exec, exec, s[4:5]
	s_mov_b64 s[4:5], exec
	v_mbcnt_lo_u32_b32 v0, s4, 0
	v_mbcnt_hi_u32_b32 v0, s5, v0
	v_cmp_eq_u32_e32 vcc, 0, v0
	s_waitcnt vmcnt(0)
	s_and_saveexec_b64 s[6:7], vcc
	s_cbranch_execz .LBB0_346
	s_bcnt1_i32_b64 s4, s[4:5]
	v_mov_b32_e32 v0, s4
	v_readlane_b32 s4, v252, 16
	v_readlane_b32 s5, v252, 17
	s_nop 4
	global_atomic_add v3, v0, s[4:5]
.LBB0_346:
	s_or_b64 exec, exec, s[6:7]
	buffer_inv sc1
	s_waitcnt vmcnt(0)

.LBB0_613:
	s_or_b64 exec, exec, s[4:5]
	s_mov_b64 s[4:5], exec
	v_mbcnt_lo_u32_b32 v0, s4, 0
	v_mbcnt_hi_u32_b32 v0, s5, v0
	v_cmp_eq_u32_e32 vcc, 0, v0
	s_waitcnt vmcnt(0)
	s_and_saveexec_b64 s[8:9], vcc
	s_cbranch_execz .LBB0_615
	s_bcnt1_i32_b64 s4, s[4:5]
	v_mov_b32_e32 v0, s4
	v_readlane_b32 s4, v252, 16
	v_readlane_b32 s5, v252, 17
	s_nop 4
	global_atomic_add v3, v0, s[4:5]
.LBB0_615:
	s_or_b64 exec, exec, s[8:9]
	buffer_inv sc1
	s_waitcnt vmcnt(0)

.LBB0_1158:
	s_or_b64 exec, exec, s[8:9]
	s_mov_b64 s[8:9], exec
	v_mbcnt_lo_u32_b32 v0, s8, 0
	v_mbcnt_hi_u32_b32 v0, s9, v0
	v_cmp_eq_u32_e32 vcc, 0, v0
	s_waitcnt vmcnt(0)
	s_and_saveexec_b64 s[10:11], vcc
	s_cbranch_execz .LBB0_1160
	s_bcnt1_i32_b64 s8, s[8:9]
	v_mov_b32_e32 v0, s8
	v_readlane_b32 s8, v252, 16
	v_readlane_b32 s9, v252, 17
	s_nop 4
	global_atomic_add v3, v0, s[8:9]
.LBB0_1160:
	s_or_b64 exec, exec, s[10:11]
	buffer_inv sc1
	s_waitcnt vmcnt(0)

.LBB0_1574:
	s_or_b64 exec, exec, s[2:3]
	s_mov_b64 s[2:3], exec
	v_mbcnt_lo_u32_b32 v0, s2, 0
	v_mbcnt_hi_u32_b32 v0, s3, v0
	v_cmp_eq_u32_e32 vcc, 0, v0
	s_waitcnt vmcnt(0)
	s_and_saveexec_b64 s[4:5], vcc
	s_cbranch_execnz .LBB0_1575
	s_getpc_b64 s[98:99]
